# as S12 with the DMA address arithmetic and the four LDS-DMA issues moved from the QK MFMA block into the P.V MFMA block
# baseline (speedup 1.0000x reference)
; __device__ __forceinline__ void finishSM(f32x16& p0, f32x16& p1, float alpha, float& l_reg, bf16x8& pa0, bf16x8& pa1, bf16x8& pa2, bf16x8& pa3) {
;   for (int r = 0; r < 16; ++r) p1[r] = __builtin_amdgcn_exp2f(p1[r]);
;   float ps = 0; for (int r = 0; r < 16; ++r) ps += p0[r]; for (int r = 0; r < 16; ++r) ps += p1[r];
;   { auto rr = __builtin_amdgcn_permlane32_swap(__float_as_uint(ps), __float_as_uint(ps), false, false);
;     ps = __uint_as_float(rr[0]) + __uint_as_float(rr[1]); }
;   l_reg = l_reg * alpha + ps;
;     ...
;   PK4(p0, 0, pa0); PK4(p0, 8, pa1); PK4(p1, 0, pa2); PK4(p1, 8, pa3);
;     ...
; }
; __device__ __forceinline__ void kload(bf16x8 (&kf)[8], const char* Ks, int r32, int hi, int sb) {
; #pragma unroll
;   for (int d0 = 0; d0 < 4; ++d0) { const int cb = sb + (d0 * 16 + hi * 8) * 2;
;     kf[2 * d0] = *reinterpret_cast<const bf16x8*>(Ks + KSWZ(r32, cb)); kf[2 * d0 + 1] = *reinterpret_cast<const bf16x8*>(Ks + KSWZ(32 + r32, cb)); }
; }
; __device__ __forceinline__ void kmma(f32x16& p0, f32x16& p1, const bf16x8 (&kf)[8], const bf16x8* qr) {
;   asm volatile("s_waitcnt lgkmcnt(0)" ::: "memory"); SBAR();
;   p0 = f32x16{}; p1 = f32x16{};
; #pragma unroll
;   for (int d0 = 0; d0 < 4; ++d0) { p0 = __builtin_amdgcn_mfma_f32_32x32x16_bf16(kf[2 * d0], qr[d0], p0, 0, 0, 0); p1 = __builtin_amdgcn_mfma_f32_32x32x16_bf16(kf[2 * d0 + 1], qr[d0], p1, 0, 0, 0); }
; }
; __device__ __forceinline__ void qkt(f32x16& p0, f32x16& p1, const char* Ks, const bf16x8* qr, int r32, int hi, int sb) {
;   bf16x8 kf[8]; kload(kf, Ks, r32, hi, sb); SBAR(); kmma(p0, p1, kf, qr);
; }
; __device__ __forceinline__ int v_st(int k, int c) { const int kk = (k & ~0xC) | ((k & 4) << 1) | ((k & 8) >> 1); return ((kk >> 3) * 4 + (c >> 5)) * 512 + ((kk & 7) * 32 + (c & 31)) * 2; }
; __device__ __forceinline__ int v_rd_base(int lane) { return ((lane & 3) << 3) | (((lane >> 2) & 3) << 6) | (((lane >> 4) & 1) << 5) | (((lane >> 5) & 1) << 8); }
; template <int OFF> __device__ __forceinline__ s16x4 tr_read(int vb) {
;   s16x4 r; asm volatile("ds_read_b64_tr_b16 %0, %1 offset:%2" : "=&v"(r) : "v"(vb), "i"(OFF) : "memory"); return r;
; }
; template <int D0> __device__ __forceinline__ void v_frag_read(VFrag& f, int vb) {
;   f.l0 = tr_read<v_rd_off(D0, 0, 0)>(vb); f.h0 = tr_read<v_rd_off(D0, 0, 1)>(vb); f.l1 = tr_read<v_rd_off(D0, 1, 0)>(vb); f.h1 = tr_read<v_rd_off(D0, 1, 1)>(vb);
.LBB0_770:
	ds_read_b128 v[82:85], v245
	ds_read_b128 v[86:89], v245 offset:8192
	ds_read_b128 v[130:133], v246
	ds_read_b128 v[134:137], v246 offset:8192
	ds_read_b128 v[206:209], v247
	ds_read_b128 v[210:213], v247 offset:8192
	ds_read_b128 v[214:217], v255
	ds_read_b128 v[218:221], v255 offset:8192
	v_exp_f32_e32 v148, v66
	v_add_f32_e32 v66, 0, v175
	v_add_f32_e32 v66, v177, v66
	v_add_f32_e32 v66, v192, v66
	v_add_f32_e32 v66, v195, v66
	v_add_f32_e32 v66, v196, v66
	v_add_f32_e32 v66, v199, v66
	v_add_f32_e32 v66, v200, v66
	v_add_f32_e32 v66, v203, v66
	v_add_f32_e32 v66, v176, v66
	v_add_f32_e32 v66, v193, v66
	v_add_f32_e32 v66, v194, v66
	v_add_f32_e32 v66, v197, v66
	v_add_f32_e32 v66, v198, v66
	v_exp_f32_e32 v149, v67
	v_add_f32_e32 v66, v201, v66
	s_waitcnt lgkmcnt(7)
	v_mfma_f32_32x32x16_bf16 v[98:113], v[82:85], v[126:129], 0
	v_exp_f32_e32 v150, v68
	s_and_b32 s13, s36, 0xc000
	v_add_f32_e32 v66, v202, v66
	v_exp_f32_e32 v151, v69
	v_add_f32_e32 v66, v204, v66
	s_waitcnt lgkmcnt(6)
	v_mfma_f32_32x32x16_bf16 v[82:97], v[86:89], v[126:129], 0
	v_exp_f32_e32 v186, v70
	v_add_u32_e32 v244, s13, v164
	v_add_f32_e32 v66, v148, v66
	v_exp_f32_e32 v187, v71
	v_add_f32_e32 v66, v149, v66
	v_exp_f32_e32 v188, v72
	s_waitcnt lgkmcnt(5)
	v_mfma_f32_32x32x16_bf16 v[98:113], v[130:133], v[122:125], v[98:113]
	v_add_f32_e32 v66, v150, v66
	ds_read_b64_tr_b16 v[228:229], v244 offset:0
	v_exp_f32_e32 v189, v73
	v_add_f32_e32 v66, v151, v66
	v_exp_f32_e32 v205, v74
	s_waitcnt lgkmcnt(5)
	v_mfma_f32_32x32x16_bf16 v[82:97], v[134:137], v[122:125], v[82:97]
	v_add_f32_e32 v66, v186, v66
	ds_read_b64_tr_b16 v[230:231], v244 offset:0x800
	v_exp_f32_e32 v222, v75
	ds_read_b64_tr_b16 v[232:233], v244 offset:0x1000
	v_add_f32_e32 v66, v187, v66
	v_exp_f32_e32 v223, v76
	v_add_f32_e32 v66, v188, v66
	s_waitcnt lgkmcnt(6)
	v_mfma_f32_32x32x16_bf16 v[98:113], v[206:209], v[118:121], v[98:113]
	v_exp_f32_e32 v224, v77
	ds_read_b64_tr_b16 v[234:235], v244 offset:0x1800
	v_add_f32_e32 v66, v189, v66
	v_exp_f32_e32 v225, v78
	v_add_f32_e32 v66, v205, v66
	s_waitcnt lgkmcnt(6)
	v_mfma_f32_32x32x16_bf16 v[82:97], v[210:213], v[118:121], v[82:97]
	v_exp_f32_e32 v226, v79
	ds_read_b64_tr_b16 v[236:237], v244 offset:0x2000
	v_add_f32_e32 v66, v222, v66
	v_exp_f32_e32 v227, v80
	v_add_f32_e32 v66, v223, v66
	v_exp_f32_e32 v81, v81
	s_waitcnt lgkmcnt(6)
	v_mfma_f32_32x32x16_bf16 v[98:113], v[214:217], v[114:117], v[98:113]
	v_add_f32_e32 v66, v224, v66
	ds_read_b64_tr_b16 v[238:239], v244 offset:0x2800
	v_add_f32_e32 v66, v225, v66
	v_add_f32_e32 v66, v226, v66
	v_add_f32_e32 v66, v227, v66
	s_waitcnt lgkmcnt(6)
	v_mfma_f32_32x32x16_bf16 v[82:97], v[218:221], v[114:117], v[82:97]
	v_add_f32_e32 v130, v81, v66
	ds_read_b64_tr_b16 v[240:241], v244 offset:0x3000
	v_mov_b32_e32 v131, v130
	ds_read_b64_tr_b16 v[242:243], v244 offset:0x3800
	v_cvt_pk_bf16_f32 v66, v175, v177
	v_cvt_pk_bf16_f32 v67, v192, v195
	v_cvt_pk_bf16_f32 v68, v196, v199
	v_permlane32_swap_b32_e32 v130, v131
	v_cvt_pk_bf16_f32 v69, v200, v203
	v_permlane32_swap_b32_e32 v66, v68
	v_cvt_pk_bf16_f32 v70, v176, v193
	v_cvt_pk_bf16_f32 v71, v194, v197
	v_cvt_pk_bf16_f32 v72, v198, v201
	v_cvt_pk_bf16_f32 v73, v202, v204
	v_cvt_pk_bf16_f32 v74, v148, v149
	v_cvt_pk_bf16_f32 v75, v150, v151
	v_cvt_pk_bf16_f32 v76, v186, v187
	v_cvt_pk_bf16_f32 v77, v188, v189
	v_cvt_pk_bf16_f32 v78, v205, v222
	v_cvt_pk_bf16_f32 v79, v223, v224
	v_cvt_pk_bf16_f32 v80, v225, v226
	v_cvt_pk_bf16_f32 v81, v227, v81
	v_permlane32_swap_b32_e32 v67, v69
	v_permlane32_swap_b32_e32 v70, v72
	v_permlane32_swap_b32_e32 v71, v73
	v_permlane32_swap_b32_e32 v74, v76
	v_permlane32_swap_b32_e32 v75, v77
	v_permlane32_swap_b32_e32 v78, v80
	v_permlane32_swap_b32_e32 v79, v81
	ds_read_b64_tr_b16 v[204:205], v244 offset:0x200
	ds_read_b64_tr_b16 v[206:207], v244 offset:0xa00
	ds_read_b64_tr_b16 v[208:209], v244 offset:0x1200
	ds_read_b64_tr_b16 v[210:211], v244 offset:0x1a00
	ds_read_b64_tr_b16 v[212:213], v244 offset:0x2200
	ds_read_b64_tr_b16 v[214:215], v244 offset:0x2a00
	ds_read_b64_tr_b16 v[216:217], v244 offset:0x3200
	ds_read_b64_tr_b16 v[218:219], v244 offset:0x3a00
	s_waitcnt lgkmcnt(14)
	v_mfma_f32_32x32x16_bf16 v[18:33], v[66:69], v[228:231], v[18:33]
	v_max_f32_e32 v245, v99, v99
	s_add_i32 s37, s12, 2
	v_max_f32_e32 v246, v98, v98
	s_cmpk_lt_u32 s12, 0x7e
	v_max_f32_e32 v245, v246, v245
	s_cselect_b64 s[44:45], -1, 0
	v_max3_f32 v245, v245, v100, v101
	v_max3_f32 v245, v245, v102, v103
	v_max3_f32 v245, v245, v104, v105
	s_waitcnt lgkmcnt(12)
	v_mfma_f32_32x32x16_bf16 v[18:33], v[70:73], v[232:235], v[18:33]
	v_max3_f32 v245, v245, v106, v107
	s_and_b64 s[46:47], s[44:45], exec
	v_max3_f32 v245, v245, v108, v109
	s_cselect_b32 s46, 0, 0xffffff80
	v_max3_f32 v245, v245, v110, v111
	s_add_i32 s58, s37, s46
	v_max3_f32 v245, v245, v112, v113
	v_max3_f32 v245, v245, v82, v83
	v_max3_f32 v245, v245, v84, v85
	v_max3_f32 v245, v245, v86, v87
	s_waitcnt lgkmcnt(10)
	v_mfma_f32_32x32x16_bf16 v[18:33], v[74:77], v[236:239], v[18:33]
	v_max3_f32 v245, v245, v88, v89
	s_and_b64 s[44:45], s[44:45], exec
	v_max3_f32 v245, v245, v90, v91
	s_cselect_b32 s45, s9, s30
	v_max3_f32 v245, v245, v92, v93
	s_cselect_b32 s44, s8, s26
	v_max3_f32 v245, v245, v94, v95
	v_max3_f32 v245, v245, v96, v97
	v_mov_b32_e32 v246, v245
	s_nop 1
	v_permlane32_swap_b32_e32 v245, v246
	s_waitcnt lgkmcnt(8)
; #define SBAR() __builtin_amdgcn_sched_barrier(0)
; __device__ __forceinline__ void pv_d0(f32x16* o, int vb, bf16x8 pa0, bf16x8 pa1, bf16x8 pa2, bf16x8 pa3) {
;   VFrag fa, fb;
;   v_frag_read<0>(fa, vb);
;   asm volatile("s_waitcnt lgkmcnt(0)" ::: "memory"); SBAR();
;   v_frag_read<1>(fb, vb); SBAR();
;   pv_mma(o[0], fa, pa0, pa1, pa2, pa3); SBAR();
;   asm volatile("s_waitcnt lgkmcnt(0)" ::: "memory"); SBAR();
;   v_frag_read<2>(fa, vb); SBAR();
;   pv_mma(o[1], fb, pa0, pa1, pa2, pa3); SBAR();
;   asm volatile("s_waitcnt lgkmcnt(0)" ::: "memory"); SBAR();
;   v_frag_read<3>(fb, vb); SBAR();
;   pv_mma(o[2], fa, pa0, pa1, pa2, pa3); SBAR();
;   asm volatile("s_waitcnt lgkmcnt(0)" ::: "memory"); SBAR();
;   pv_mma(o[3], fb, pa0, pa1, pa2, pa3);
; }
	v_mfma_f32_32x32x16_bf16 v[18:33], v[78:81], v[240:243], v[18:33]
	v_max_f32_e32 v246, v246, v246
	s_lshl_b64 s[46:47], s[58:59], 17
	v_max_f32_e32 v245, v245, v245
	s_lshl_b64 s[44:45], s[44:45], 11
	v_max_f32_e32 v245, v245, v246
	s_add_u32 s46, s46, s44
	v_sub_f32_e32 v246, v245, v174
	s_addc_u32 s47, s47, s45
	v_cmp_ge_f32_e32 vcc, s63, v246
	v_max_f32_e32 v246, v174, v174
	v_max_f32_e32 v245, v246, v245
	v_sub_f32_e32 v246, v174, v245
	v_mul_f32_e32 v246, 0x3e38aa3b, v246
	v_exp_f32_e32 v246, v246
	s_cmp_eq_u64 vcc, exec
	s_cselect_b64 s[0:1], -1, 0
	v_cndmask_b32_e64 v132, v246, 1.0, s[0:1]
	ds_read_b64_tr_b16 v[228:229], v244 offset:0x400
	ds_read_b64_tr_b16 v[230:231], v244 offset:0xc00
	ds_read_b64_tr_b16 v[232:233], v244 offset:0x1400
	ds_read_b64_tr_b16 v[234:235], v244 offset:0x1c00
	ds_read_b64_tr_b16 v[236:237], v244 offset:0x2400
	ds_read_b64_tr_b16 v[238:239], v244 offset:0x2c00
	ds_read_b64_tr_b16 v[240:241], v244 offset:0x3400
	ds_read_b64_tr_b16 v[242:243], v244 offset:0x3c00
	v_cndmask_b32_e64 v133, v245, v174, s[0:1]
	v_mul_f32_e32 v148, 0xbe38aa3b, v133
	s_waitcnt lgkmcnt(14)
	v_mfma_f32_32x32x16_bf16 v[50:65], v[66:69], v[204:207], v[50:65]
	v_fmamk_f32 v98, v98, 0x3e38aa3b, v148
	s_add_u32 s44, s20, s46
	v_fmamk_f32 v99, v99, 0x3e38aa3b, v148
	s_addc_u32 s45, s21, s47
	v_fmamk_f32 v100, v100, 0x3e38aa3b, v148
	s_add_u32 s46, s22, s46
	v_fmamk_f32 v101, v101, 0x3e38aa3b, v148
	s_waitcnt lgkmcnt(12)
	v_mfma_f32_32x32x16_bf16 v[50:65], v[70:73], v[208:211], v[50:65]
	v_fmamk_f32 v102, v102, 0x3e38aa3b, v148
	s_addc_u32 s47, s23, s47
	v_fmamk_f32 v103, v103, 0x3e38aa3b, v148
	s_and_b32 s43, s37, 0xff
	v_fmamk_f32 v104, v104, 0x3e38aa3b, v148
	s_mulk_i32 s43, 0xab
	v_fmamk_f32 v105, v105, 0x3e38aa3b, v148
	s_lshr_b32 s43, s43, 9
	s_waitcnt lgkmcnt(10)
	v_mfma_f32_32x32x16_bf16 v[50:65], v[74:77], v[212:215], v[50:65]
	v_fmamk_f32 v106, v106, 0x3e38aa3b, v148
	s_mul_i32 s43, s43, 3
	v_fmamk_f32 v107, v107, 0x3e38aa3b, v148
	s_sub_i32 s43, s37, s43
	v_fmamk_f32 v108, v108, 0x3e38aa3b, v148
	s_and_b32 s43, s43, 0xff
	v_fmamk_f32 v109, v109, 0x3e38aa3b, v148
	s_lshl_b32 s43, s43, 14
	s_mov_b32 s100, s43
	s_waitcnt lgkmcnt(8)
	v_mfma_f32_32x32x16_bf16 v[50:65], v[78:81], v[216:219], v[50:65]
	v_fmamk_f32 v110, v110, 0x3e38aa3b, v148
	s_add_i32 s42, s36, 0xffffc000
	v_fmamk_f32 v111, v111, 0x3e38aa3b, v148
	s_and_b32 s42, s42, 0xc000
	v_fmamk_f32 v112, v112, 0x3e38aa3b, v148
	s_add_i32 s43, s43, s27
	v_fmamk_f32 v113, v113, 0x3e38aa3b, v148
	s_add_i32 s42, s42, s31
	ds_read_b64_tr_b16 v[204:205], v244 offset:0x600
	ds_read_b64_tr_b16 v[206:207], v244 offset:0xe00
	ds_read_b64_tr_b16 v[208:209], v244 offset:0x1600
	ds_read_b64_tr_b16 v[210:211], v244 offset:0x1e00
	ds_read_b64_tr_b16 v[212:213], v244 offset:0x2600
	ds_read_b64_tr_b16 v[214:215], v244 offset:0x2e00
	ds_read_b64_tr_b16 v[216:217], v244 offset:0x3600
	ds_read_b64_tr_b16 v[218:219], v244 offset:0x3e00
	s_waitcnt lgkmcnt(14)
	v_mfma_f32_32x32x16_bf16 v[34:49], v[66:69], v[228:231], v[34:49]
	v_fmamk_f32 v82, v82, 0x3e38aa3b, v148
	v_lshl_add_u64 v[246:247], s[44:45], 0, v[146:147]
	v_fmamk_f32 v83, v83, 0x3e38aa3b, v148
	s_mov_b32 m0, s43
	v_fmamk_f32 v84, v84, 0x3e38aa3b, v148
	global_load_lds_dwordx4 v[246:247], off
	s_waitcnt lgkmcnt(12)
	v_mfma_f32_32x32x16_bf16 v[34:49], v[70:73], v[232:235], v[34:49]
	v_fmamk_f32 v85, v85, 0x3e38aa3b, v148
	v_lshl_add_u64 v[246:247], s[46:47], 0, v[142:143]
	v_fmamk_f32 v86, v86, 0x3e38aa3b, v148
	s_mov_b32 m0, s42
	v_fmamk_f32 v87, v87, 0x3e38aa3b, v148
	global_load_lds_dwordx4 v[246:247], off
	s_add_i32 s13, s36, 0xffff4000
	s_waitcnt lgkmcnt(10)
	v_mfma_f32_32x32x16_bf16 v[34:49], v[74:77], v[236:239], v[34:49]
	v_fmamk_f32 v149, v88, 0x3e38aa3b, v148
	v_lshl_add_u64 v[246:247], s[44:45], 0, v[144:145]
	v_fmamk_f32 v150, v89, 0x3e38aa3b, v148
	s_add_i32 m0, s43, 0x2000
	v_fmamk_f32 v151, v90, 0x3e38aa3b, v148
	global_load_lds_dwordx4 v[246:247], off
	s_waitcnt lgkmcnt(8)
	v_mfma_f32_32x32x16_bf16 v[34:49], v[78:81], v[240:243], v[34:49]
	v_fmamk_f32 v186, v91, 0x3e38aa3b, v148
	v_lshl_add_u64 v[246:247], s[46:47], 0, v[154:155]
	v_fmamk_f32 v187, v92, 0x3e38aa3b, v148
	s_add_i32 m0, s42, 0x2000
	v_fmamk_f32 v188, v93, 0x3e38aa3b, v148
	global_load_lds_dwordx4 v[246:247], off
	v_fmamk_f32 v189, v94, 0x3e38aa3b, v148
	v_exp_f32_e32 v192, v98
	v_exp_f32_e32 v193, v99
	v_exp_f32_e32 v194, v100
	v_exp_f32_e32 v195, v101
	s_waitcnt lgkmcnt(6)
	v_mfma_f32_32x32x16_bf16 v[2:17], v[66:69], v[204:207], v[2:17]
	v_exp_f32_e32 v196, v102
	v_exp_f32_e32 v197, v103
	v_exp_f32_e32 v198, v104
	v_exp_f32_e32 v199, v105
	s_waitcnt lgkmcnt(4)
	v_mfma_f32_32x32x16_bf16 v[2:17], v[70:73], v[208:211], v[2:17]
	v_exp_f32_e32 v200, v106
	v_exp_f32_e32 v201, v107
	v_exp_f32_e32 v202, v108
	v_exp_f32_e32 v203, v109
	v_exp_f32_e32 v204, v110
	v_exp_f32_e32 v205, v111
	s_waitcnt lgkmcnt(2)
	v_mfma_f32_32x32x16_bf16 v[2:17], v[74:77], v[212:215], v[2:17]
	v_exp_f32_e32 v206, v112
	v_exp_f32_e32 v207, v113
	v_fmamk_f32 v208, v95, 0x3e38aa3b, v148
	v_fmamk_f32 v209, v96, 0x3e38aa3b, v148
	v_fmac_f32_e32 v148, 0x3e38aa3b, v97
	s_waitcnt lgkmcnt(0)
	v_mfma_f32_32x32x16_bf16 v[2:17], v[78:81], v[216:219], v[2:17]
	v_add_u32_e32 v245, s101, v169
	v_add_u32_e32 v246, s101, v170
	v_add_u32_e32 v247, s101, v171
	v_add_u32_e32 v244, s101, v172
	v_cmp_gt_f32_e32 vcc, 1.0, v132
	s_cbranch_vccz .LBB0_774
; #define SBAR() __builtin_amdgcn_sched_barrier(0)
; __device__ __forceinline__ void attn_unit(const bf16* __restrict__ Qb, const bf16* __restrict__ Kh, const bf16* __restrict__ Vh, int klat0, int nlt, int kctx0, int NT,
;                                           float lam, float post, const float* __restrict__ subw, bf16* __restrict__ Ob, char* lds) {
;     ...
;       if (j + 3 < NT) DMA_TILE(j + 3);
;       SBAR(); qkt(pA0, pA1, KS(j + 1), qr, r32, hi, sb);
	s_and_saveexec_b64 s[10:11], s[40:41]
	ds_write_b32 v162, v132 offset:128
	s_or_b64 exec, exec, s[10:11]
	s_waitcnt lgkmcnt(0)
	v_add_u32_e32 v67, s18, v140
	ds_read_b128 v[68:71], v67 offset:224
	ds_read_b128 v[72:75], v67 offset:192
	ds_read_b128 v[76:79], v67 offset:160
	ds_read_b128 v[134:137], v67 offset:128
	s_waitcnt lgkmcnt(0)
	v_pk_mul_f32 v[30:31], v[30:31], v[68:69]
	v_pk_mul_f32 v[26:27], v[26:27], v[72:73]
	v_pk_mul_f32 v[22:23], v[22:23], v[76:77]
	v_pk_mul_f32 v[32:33], v[32:33], v[70:71]
	v_pk_mul_f32 v[28:29], v[28:29], v[74:75]
	v_pk_mul_f32 v[24:25], v[24:25], v[78:79]
	v_pk_mul_f32 v[20:21], v[20:21], v[136:137]
	v_pk_mul_f32 v[18:19], v[18:19], v[134:135]
	v_pk_mul_f32 v[62:63], v[62:63], v[68:69]
	v_pk_mul_f32 v[58:59], v[58:59], v[72:73]
	v_pk_mul_f32 v[54:55], v[54:55], v[76:77]
	v_pk_mul_f32 v[64:65], v[64:65], v[70:71]
	v_pk_mul_f32 v[60:61], v[60:61], v[74:75]
	v_pk_mul_f32 v[56:57], v[56:57], v[78:79]
	v_pk_mul_f32 v[52:53], v[52:53], v[136:137]
	v_pk_mul_f32 v[50:51], v[50:51], v[134:135]
	v_pk_mul_f32 v[46:47], v[46:47], v[68:69]
	v_pk_mul_f32 v[42:43], v[42:43], v[72:73]
	v_pk_mul_f32 v[38:39], v[38:39], v[76:77]
	v_pk_mul_f32 v[48:49], v[48:49], v[70:71]
	v_pk_mul_f32 v[44:45], v[44:45], v[74:75]
	v_pk_mul_f32 v[40:41], v[40:41], v[78:79]
	v_pk_mul_f32 v[36:37], v[36:37], v[136:137]
	v_pk_mul_f32 v[34:35], v[34:35], v[134:135]
	v_pk_mul_f32 v[14:15], v[14:15], v[68:69]
	v_pk_mul_f32 v[10:11], v[10:11], v[72:73]
	v_pk_mul_f32 v[6:7], v[6:7], v[76:77]
	v_pk_mul_f32 v[16:17], v[16:17], v[70:71]
	v_pk_mul_f32 v[12:13], v[12:13], v[74:75]
	v_pk_mul_f32 v[8:9], v[8:9], v[78:79]
	v_pk_mul_f32 v[4:5], v[4:5], v[136:137]
	v_pk_mul_f32 v[2:3], v[2:3], v[134:135]
.LBB0_774:
	s_waitcnt vmcnt(4)
	s_barrier
	ds_read_b128 v[66:69], v245
	ds_read_b128 v[70:73], v245 offset:8192
	ds_read_b128 v[98:101], v246
	ds_read_b128 v[102:105], v246 offset:8192
	ds_read_b128 v[106:109], v247
	ds_read_b128 v[110:113], v247 offset:8192
	ds_read_b128 v[134:137], v244
	ds_read_b128 v[174:177], v244 offset:8192
	v_exp_f32_e32 v210, v82
	v_exp_f32_e32 v211, v83
	v_exp_f32_e32 v212, v84
	v_exp_f32_e32 v213, v85
	v_exp_f32_e32 v214, v86
	v_exp_f32_e32 v215, v87
	v_add_f32_e32 v216, 0, v192
	v_add_f32_e32 v216, v193, v216
	v_add_f32_e32 v216, v194, v216
	v_add_f32_e32 v216, v195, v216
	v_exp_f32_e32 v149, v149
	v_exp_f32_e32 v150, v150
	v_exp_f32_e32 v151, v151
	v_exp_f32_e32 v186, v186
	v_exp_f32_e32 v187, v187
	v_exp_f32_e32 v188, v188
	s_waitcnt lgkmcnt(7)
	v_mfma_f32_32x32x16_bf16 v[82:97], v[66:69], v[126:129], 0
	v_exp_f32_e32 v189, v189
	s_and_b32 s46, s13, 0xc000
	v_exp_f32_e32 v208, v208
	v_exp_f32_e32 v209, v209
	v_exp_f32_e32 v148, v148
	s_waitcnt lgkmcnt(6)
	v_mfma_f32_32x32x16_bf16 v[66:81], v[70:73], v[126:129], 0
	v_add_f32_e32 v255, v196, v216
	v_add_u32_e32 v244, s46, v164
	v_add_f32_e32 v255, v197, v255
	v_add_f32_e32 v255, v198, v255
	v_add_f32_e32 v255, v199, v255
	v_add_f32_e32 v255, v200, v255
	s_waitcnt lgkmcnt(5)
	v_mfma_f32_32x32x16_bf16 v[82:97], v[98:101], v[122:125], v[82:97]
	v_add_f32_e32 v255, v201, v255
	ds_read_b64_tr_b16 v[228:229], v244 offset:0
	v_add_f32_e32 v255, v202, v255
	ds_read_b64_tr_b16 v[230:231], v244 offset:0x800
	v_add_f32_e32 v255, v203, v255
	v_add_f32_e32 v255, v204, v255
	s_waitcnt lgkmcnt(6)
	v_mfma_f32_32x32x16_bf16 v[66:81], v[102:105], v[122:125], v[66:81]
	v_add_f32_e32 v255, v205, v255
	ds_read_b64_tr_b16 v[232:233], v244 offset:0x1000
	v_add_f32_e32 v255, v206, v255
	v_add_f32_e32 v255, v207, v255
	v_add_f32_e32 v255, v210, v255
	v_add_f32_e32 v255, v211, v255
	s_waitcnt lgkmcnt(6)
	v_mfma_f32_32x32x16_bf16 v[82:97], v[106:109], v[118:121], v[82:97]
	v_add_f32_e32 v255, v212, v255
	ds_read_b64_tr_b16 v[234:235], v244 offset:0x1800
	v_add_f32_e32 v255, v213, v255
	ds_read_b64_tr_b16 v[236:237], v244 offset:0x2000
	v_add_f32_e32 v255, v214, v255
	v_add_f32_e32 v255, v215, v255
	s_waitcnt lgkmcnt(7)
	v_mfma_f32_32x32x16_bf16 v[66:81], v[110:113], v[118:121], v[66:81]
	v_add_f32_e32 v255, v149, v255
	ds_read_b64_tr_b16 v[238:239], v244 offset:0x2800
	v_add_f32_e32 v255, v150, v255
	v_add_f32_e32 v255, v151, v255
	v_add_f32_e32 v255, v186, v255
	v_add_f32_e32 v255, v187, v255
	s_waitcnt lgkmcnt(7)
	v_mfma_f32_32x32x16_bf16 v[82:97], v[134:137], v[114:117], v[82:97]
	v_add_f32_e32 v255, v188, v255
	ds_read_b64_tr_b16 v[240:241], v244 offset:0x3000
	v_add_f32_e32 v255, v189, v255
	ds_read_b64_tr_b16 v[242:243], v244 offset:0x3800
	v_add_f32_e32 v255, v208, v255
	v_add_f32_e32 v255, v209, v255
	v_add_f32_e32 v99, v148, v255
	v_mov_b32_e32 v100, v99
	s_nop 1
	v_permlane32_swap_b32_e32 v99, v100
	v_cvt_pk_bf16_f32 v102, v192, v193
	v_cvt_pk_bf16_f32 v103, v194, v195
	v_cvt_pk_bf16_f32 v104, v196, v197
	v_cvt_pk_bf16_f32 v105, v198, v199
	s_waitcnt lgkmcnt(8)
	v_mfma_f32_32x32x16_bf16 v[66:81], v[174:177], v[114:117], v[66:81]
	v_cvt_pk_bf16_f32 v106, v200, v201
	v_cvt_pk_bf16_f32 v107, v202, v203
	v_cvt_pk_bf16_f32 v108, v204, v205
	v_cvt_pk_bf16_f32 v109, v206, v207
	v_cvt_pk_bf16_f32 v110, v210, v211
	v_cvt_pk_bf16_f32 v111, v212, v213
	v_cvt_pk_bf16_f32 v112, v214, v215
	v_cvt_pk_bf16_f32 v113, v149, v150
	v_cvt_pk_bf16_f32 v134, v151, v186
	v_cvt_pk_bf16_f32 v135, v187, v188
	v_cvt_pk_bf16_f32 v136, v189, v208
	v_cvt_pk_bf16_f32 v137, v209, v148
	v_permlane32_swap_b32_e32 v102, v104
	v_permlane32_swap_b32_e32 v103, v105
	v_permlane32_swap_b32_e32 v106, v108
	v_permlane32_swap_b32_e32 v107, v109
	v_permlane32_swap_b32_e32 v110, v112
	v_permlane32_swap_b32_e32 v111, v113
	v_permlane32_swap_b32_e32 v134, v136
	v_permlane32_swap_b32_e32 v135, v137
	ds_read_b64_tr_b16 v[204:205], v244 offset:0x200
	ds_read_b64_tr_b16 v[206:207], v244 offset:0xa00
	ds_read_b64_tr_b16 v[208:209], v244 offset:0x1200
	ds_read_b64_tr_b16 v[210:211], v244 offset:0x1a00
	ds_read_b64_tr_b16 v[212:213], v244 offset:0x2200
	ds_read_b64_tr_b16 v[214:215], v244 offset:0x2a00
	ds_read_b64_tr_b16 v[216:217], v244 offset:0x3200
	ds_read_b64_tr_b16 v[218:219], v244 offset:0x3a00
	s_waitcnt lgkmcnt(14)
; __device__ __forceinline__ void partialSM(f32x16& p0, f32x16& p1, float& m_reg, float& mn, float& alpha) {
;   constexpr float C = SCALE * 1.4426950408889634f;
;   float pmax = p0[0]; for (int r = 1; r < 16; ++r) pmax = fmaxf(pmax, p0[r]); for (int r = 0; r < 16; ++r) pmax = fmaxf(pmax, p1[r]);
;   { auto rr = __builtin_amdgcn_permlane32_swap(__float_as_uint(pmax), __float_as_uint(pmax), false, false);
;     pmax = fmaxf(__uint_as_float(rr[0]), __uint_as_float(rr[1])); }
;   if (__builtin_expect(__all(pmax - m_reg <= THR / SCALE), 1)) { mn = m_reg; alpha = 1.f; }
;   else { mn = fmaxf(m_reg, pmax); alpha = __builtin_amdgcn_exp2f((m_reg - mn) * C); m_reg = mn; }
;   float mnC = -mn * C;
;   for (int r = 0; r < 16; ++r) p0[r] = fmaf(p0[r], C, mnC); for (int r = 0; r < 16; ++r) p1[r] = fmaf(p1[r], C, mnC);
	v_mfma_f32_32x32x16_bf16 v[18:33], v[102:105], v[228:231], v[18:33]
	v_max_f32_e32 v245, v83, v83
	s_add_i32 s46, s12, 3
	v_max_f32_e32 v246, v82, v82
	s_cmpk_lt_u32 s12, 0x7d
	v_max_f32_e32 v245, v246, v245
	s_cselect_b64 s[42:43], -1, 0
	v_max3_f32 v245, v245, v84, v85
	v_max3_f32 v245, v245, v86, v87
	v_max3_f32 v245, v245, v88, v89
	s_waitcnt lgkmcnt(12)
	v_mfma_f32_32x32x16_bf16 v[18:33], v[106:109], v[232:235], v[18:33]
	v_max3_f32 v245, v245, v90, v91
	s_and_b64 s[44:45], s[42:43], exec
	v_max3_f32 v245, v245, v92, v93
	s_cselect_b32 s44, 0, 0xffffff80
	v_max3_f32 v245, v245, v94, v95
	s_add_i32 s58, s46, s44
	v_max3_f32 v245, v245, v96, v97
	v_max3_f32 v245, v245, v66, v67
	v_max3_f32 v245, v245, v68, v69
	v_max3_f32 v245, v245, v70, v71
	s_waitcnt lgkmcnt(10)
	v_mfma_f32_32x32x16_bf16 v[18:33], v[110:113], v[236:239], v[18:33]
	v_max3_f32 v245, v245, v72, v73
	s_and_b64 s[42:43], s[42:43], exec
	v_max3_f32 v245, v245, v74, v75
	s_cselect_b32 s43, s9, s30
	v_max3_f32 v245, v245, v76, v77
	s_cselect_b32 s42, s8, s26
	v_max3_f32 v245, v245, v78, v79
	v_max3_f32 v245, v245, v80, v81
	v_mov_b32_e32 v246, v245
	s_nop 1
	v_permlane32_swap_b32_e32 v245, v246
	s_waitcnt lgkmcnt(8)
	v_mfma_f32_32x32x16_bf16 v[18:33], v[134:137], v[240:243], v[18:33]
	v_max_f32_e32 v246, v246, v246
	s_lshl_b64 s[44:45], s[58:59], 17
	v_max_f32_e32 v245, v245, v245
	s_lshl_b64 s[42:43], s[42:43], 11
	v_max_f32_e32 v245, v245, v246
	s_add_u32 s44, s44, s42
	v_sub_f32_e32 v246, v245, v133
	s_addc_u32 s45, s45, s43
	v_cmp_ge_f32_e32 vcc, s63, v246
	v_max_f32_e32 v246, v133, v133
	v_max_f32_e32 v245, v246, v245
	v_sub_f32_e32 v246, v133, v245
	v_mul_f32_e32 v246, 0x3e38aa3b, v246
	v_exp_f32_e32 v246, v246
	s_cmp_eq_u64 vcc, exec
	s_cselect_b64 s[0:1], -1, 0
	v_cndmask_b32_e64 v247, v246, 1.0, s[0:1]
	ds_read_b64_tr_b16 v[228:229], v244 offset:0x400
	ds_read_b64_tr_b16 v[230:231], v244 offset:0xc00
	ds_read_b64_tr_b16 v[232:233], v244 offset:0x1400
	ds_read_b64_tr_b16 v[234:235], v244 offset:0x1c00
	ds_read_b64_tr_b16 v[236:237], v244 offset:0x2400
	ds_read_b64_tr_b16 v[238:239], v244 offset:0x2c00
	ds_read_b64_tr_b16 v[240:241], v244 offset:0x3400
	ds_read_b64_tr_b16 v[242:243], v244 offset:0x3c00
	v_cndmask_b32_e64 v174, v245, v133, s[0:1]
	v_mul_f32_e32 v98, 0xbe38aa3b, v174
	s_waitcnt lgkmcnt(14)
	v_mfma_f32_32x32x16_bf16 v[50:65], v[102:105], v[204:207], v[50:65]
	v_fmamk_f32 v82, v82, 0x3e38aa3b, v98
	s_add_u32 s42, s20, s44
	v_fmamk_f32 v83, v83, 0x3e38aa3b, v98
	s_addc_u32 s43, s21, s45
	v_fmamk_f32 v84, v84, 0x3e38aa3b, v98
	s_add_u32 s44, s22, s44
	v_fmamk_f32 v85, v85, 0x3e38aa3b, v98
	s_waitcnt lgkmcnt(12)
	v_mfma_f32_32x32x16_bf16 v[50:65], v[106:109], v[208:211], v[50:65]
	v_fmamk_f32 v86, v86, 0x3e38aa3b, v98
	s_mul_i32 s47, s46, 0xab
	v_fmamk_f32 v87, v87, 0x3e38aa3b, v98
	s_addc_u32 s45, s23, s45
	v_fmamk_f32 v88, v88, 0x3e38aa3b, v98
	s_bfe_u32 s47, s47, 0x70009
	v_fmamk_f32 v89, v89, 0x3e38aa3b, v98
	s_waitcnt lgkmcnt(10)
	v_mfma_f32_32x32x16_bf16 v[50:65], v[110:113], v[212:215], v[50:65]
	v_fmamk_f32 v90, v90, 0x3e38aa3b, v98
	s_mul_i32 s47, s47, 3
	v_fmamk_f32 v91, v91, 0x3e38aa3b, v98
	s_sub_i32 s46, s46, s47
	v_fmamk_f32 v92, v92, 0x3e38aa3b, v98
	s_and_b32 s46, s46, 0xff
	v_fmamk_f32 v93, v93, 0x3e38aa3b, v98
	s_waitcnt lgkmcnt(8)
	v_mfma_f32_32x32x16_bf16 v[50:65], v[134:137], v[216:219], v[50:65]
	v_fmamk_f32 v94, v94, 0x3e38aa3b, v98
	s_lshl_b32 s46, s46, 14
	s_mov_b32 s101, s46
	v_fmamk_f32 v95, v95, 0x3e38aa3b, v98
	s_add_i32 s46, s46, s27
	v_fmamk_f32 v96, v96, 0x3e38aa3b, v98
	s_and_b32 s47, s36, 0xc000
	v_fmamk_f32 v97, v97, 0x3e38aa3b, v98
	s_add_i32 s47, s47, s31
	s_cmpk_gt_u32 s12, 0x80
	s_cselect_b64 s[10:11], -1, 0
	s_and_b64 vcc, exec, s[10:11]
	s_cbranch_vccnz .LBB0_776
	v_lshl_add_u64 v[222:223], s[42:43], 0, v[146:147]
	s_mov_b32 m0, s46
	s_nop 0
	global_load_lds_dwordx4 v[222:223], off
	v_lshl_add_u64 v[222:223], s[44:45], 0, v[142:143]
	s_mov_b32 m0, s47
	s_nop 0
	global_load_lds_dwordx4 v[222:223], off
	v_lshl_add_u64 v[222:223], s[42:43], 0, v[144:145]
	s_add_i32 m0, s46, 0x2000
	s_nop 0
	global_load_lds_dwordx4 v[222:223], off
	v_lshl_add_u64 v[222:223], s[44:45], 0, v[154:155]
	s_add_i32 m0, s47, 0x2000
	s_nop 0
	global_load_lds_dwordx4 v[222:223], off
; #define SBAR() __builtin_amdgcn_sched_barrier(0)
; #define TILE_BAR(n) do { asm volatile("s_waitcnt vmcnt(" #n ")" ::: "memory"); __builtin_amdgcn_s_barrier(); asm volatile("" ::: "memory"); } while (0)
; #define RESC(a) do { if (__any((a) < 1.f)) { if (hi == 0) al_l[r32] = (a); asm volatile("s_waitcnt lgkmcnt(0)" ::: "memory"); \
;     for (int d = 0; d < 4; ++d) for (int r = 0; r < 16; ++r) o[d][r] *= al_l[crow(r, hi)]; } } while (0)
; __device__ __forceinline__ void pv_d0(f32x16* o, int vb, bf16x8 pa0, bf16x8 pa1, bf16x8 pa2, bf16x8 pa3) {
;   VFrag fa, fb;
;   v_frag_read<0>(fa, vb);
;   asm volatile("s_waitcnt lgkmcnt(0)" ::: "memory"); SBAR();
;   v_frag_read<1>(fb, vb); SBAR();
;   pv_mma(o[0], fa, pa0, pa1, pa2, pa3); SBAR();
;   asm volatile("s_waitcnt lgkmcnt(0)" ::: "memory"); SBAR();
;   v_frag_read<2>(fa, vb); SBAR();
;   pv_mma(o[1], fb, pa0, pa1, pa2, pa3); SBAR();
;   asm volatile("s_waitcnt lgkmcnt(0)" ::: "memory"); SBAR();
;   v_frag_read<3>(fb, vb); SBAR();
;   pv_mma(o[2], fa, pa0, pa1, pa2, pa3); SBAR();
;   asm volatile("s_waitcnt lgkmcnt(0)" ::: "memory"); SBAR();
;   pv_mma(o[3], fb, pa0, pa1, pa2, pa3);
; }
; __device__ __forceinline__ void attn_unit(const bf16* __restrict__ Qb, const bf16* __restrict__ Kh, const bf16* __restrict__ Vh, int klat0, int nlt, int kctx0, int NT,
;                                           float lam, float post, const float* __restrict__ subw, bf16* __restrict__ Ob, char* lds) {
;     ...
;       RESC(alB);
;       if (j + 2 < NT) TILE_BAR(4); else TILE_BAR(0);
.LBB0_776:
	ds_read_b64_tr_b16 v[204:205], v244 offset:0x600
	ds_read_b64_tr_b16 v[206:207], v244 offset:0xe00
	ds_read_b64_tr_b16 v[208:209], v244 offset:0x1600
	ds_read_b64_tr_b16 v[210:211], v244 offset:0x1e00
	ds_read_b64_tr_b16 v[212:213], v244 offset:0x2600
	ds_read_b64_tr_b16 v[214:215], v244 offset:0x2e00
	ds_read_b64_tr_b16 v[216:217], v244 offset:0x3600
	ds_read_b64_tr_b16 v[218:219], v244 offset:0x3e00
	s_waitcnt lgkmcnt(14)
	v_mfma_f32_32x32x16_bf16 v[34:49], v[102:105], v[228:231], v[34:49]
	s_mov_b32 s46, 0x3e38aa3b
	v_pk_fma_f32 v[80:81], v[80:81], s[46:47], v[98:99] op_sel_hi:[1,0,0]
	v_pk_fma_f32 v[78:79], v[78:79], s[46:47], v[98:99] op_sel_hi:[1,0,0]
	s_waitcnt lgkmcnt(12)
	v_mfma_f32_32x32x16_bf16 v[34:49], v[106:109], v[232:235], v[34:49]
	v_pk_fma_f32 v[76:77], v[76:77], s[46:47], v[98:99] op_sel_hi:[1,0,0]
	v_pk_fma_f32 v[74:75], v[74:75], s[46:47], v[98:99] op_sel_hi:[1,0,0]
	v_pk_fma_f32 v[72:73], v[72:73], s[46:47], v[98:99] op_sel_hi:[1,0,0]
	s_waitcnt lgkmcnt(10)
	v_mfma_f32_32x32x16_bf16 v[34:49], v[110:113], v[236:239], v[34:49]
	v_pk_fma_f32 v[70:71], v[70:71], s[46:47], v[98:99] op_sel_hi:[1,0,0]
	v_pk_fma_f32 v[68:69], v[68:69], s[46:47], v[98:99] op_sel_hi:[1,0,0]
	v_pk_fma_f32 v[66:67], v[66:67], s[46:47], v[98:99] op_sel_hi:[1,0,0]
	s_waitcnt lgkmcnt(8)
	v_mfma_f32_32x32x16_bf16 v[34:49], v[134:137], v[240:243], v[34:49]
	v_exp_f32_e32 v175, v82
	v_exp_f32_e32 v177, v83
	v_exp_f32_e32 v192, v84
	s_waitcnt lgkmcnt(6)
	v_mfma_f32_32x32x16_bf16 v[2:17], v[102:105], v[204:207], v[2:17]
	v_mov_b32_e32 v205, v247
	v_exp_f32_e32 v204, v97
	v_exp_f32_e32 v195, v85
	v_exp_f32_e32 v196, v86
	v_exp_f32_e32 v199, v87
	v_exp_f32_e32 v200, v88
	s_waitcnt lgkmcnt(4)
	v_mfma_f32_32x32x16_bf16 v[2:17], v[106:109], v[208:211], v[2:17]
	v_exp_f32_e32 v203, v89
	v_exp_f32_e32 v176, v90
	v_exp_f32_e32 v193, v91
	v_exp_f32_e32 v194, v92
	s_waitcnt lgkmcnt(2)
	v_mfma_f32_32x32x16_bf16 v[2:17], v[110:113], v[212:215], v[2:17]
	v_exp_f32_e32 v197, v93
	v_exp_f32_e32 v198, v94
	v_exp_f32_e32 v201, v95
	v_exp_f32_e32 v202, v96
	s_waitcnt lgkmcnt(0)
	v_mfma_f32_32x32x16_bf16 v[2:17], v[134:137], v[216:219], v[2:17]
	v_add_u32_e32 v245, s100, v169
	v_add_u32_e32 v246, s100, v170
	v_add_u32_e32 v247, s100, v171
	v_add_u32_e32 v255, s100, v172
	v_cmp_gt_f32_e32 vcc, 1.0, v205
	s_cbranch_vccz .LBB0_780
	s_and_saveexec_b64 s[12:13], s[40:41]
	ds_write_b32 v162, v205 offset:128
	s_or_b64 exec, exec, s[12:13]
	s_waitcnt lgkmcnt(0)
	v_add_u32_e32 v101, s18, v140
	ds_read_b128 v[102:105], v101 offset:224
	ds_read_b128 v[106:109], v101 offset:192
	ds_read_b128 v[110:113], v101 offset:160
	ds_read_b128 v[134:137], v101 offset:128
	s_waitcnt lgkmcnt(0)
	v_pk_mul_f32 v[30:31], v[30:31], v[102:103]
	v_pk_mul_f32 v[26:27], v[26:27], v[106:107]
	v_pk_mul_f32 v[22:23], v[22:23], v[110:111]
	v_pk_mul_f32 v[32:33], v[32:33], v[104:105]
	v_pk_mul_f32 v[28:29], v[28:29], v[108:109]
	v_pk_mul_f32 v[24:25], v[24:25], v[112:113]
	v_pk_mul_f32 v[20:21], v[20:21], v[136:137]
	v_pk_mul_f32 v[18:19], v[18:19], v[134:135]
	v_pk_mul_f32 v[62:63], v[62:63], v[102:103]
	v_pk_mul_f32 v[58:59], v[58:59], v[106:107]
	v_pk_mul_f32 v[54:55], v[54:55], v[110:111]
	v_pk_mul_f32 v[64:65], v[64:65], v[104:105]
	v_pk_mul_f32 v[60:61], v[60:61], v[108:109]
	v_pk_mul_f32 v[56:57], v[56:57], v[112:113]
	v_pk_mul_f32 v[52:53], v[52:53], v[136:137]
	v_pk_mul_f32 v[50:51], v[50:51], v[134:135]
	v_pk_mul_f32 v[46:47], v[46:47], v[102:103]
	v_pk_mul_f32 v[42:43], v[42:43], v[106:107]
	v_pk_mul_f32 v[38:39], v[38:39], v[110:111]
	v_pk_mul_f32 v[48:49], v[48:49], v[104:105]
	v_pk_mul_f32 v[44:45], v[44:45], v[108:109]
	v_pk_mul_f32 v[40:41], v[40:41], v[112:113]
	v_pk_mul_f32 v[36:37], v[36:37], v[136:137]
	v_pk_mul_f32 v[34:35], v[34:35], v[134:135]
	v_pk_mul_f32 v[14:15], v[14:15], v[102:103]
	v_pk_mul_f32 v[10:11], v[10:11], v[106:107]
	v_pk_mul_f32 v[6:7], v[6:7], v[110:111]
	v_pk_mul_f32 v[16:17], v[16:17], v[104:105]
	v_pk_mul_f32 v[12:13], v[12:13], v[108:109]
	v_pk_mul_f32 v[8:9], v[8:9], v[112:113]
	v_pk_mul_f32 v[4:5], v[4:5], v[136:137]
	v_pk_mul_f32 v[2:3], v[2:3], v[134:135]
